# DSA attention: wave-uniform specialisation for tokens with the full 256 selected keys (no nsel masking in the QK post-processing and softmax), on top of the row-offset table and straight-line softmax
# speedup vs baseline: 1.0048x; 1.0048x over previous
;   __device__ __forceinline__ half_t* mm() const { return (half_t*)(ws() + OFF_mm); }
; __device__ __forceinline__ void dsa_item(const KP& p, int b, int tile, char* smem) {
;     ...
;     const int nsel = min(cnt[tk], 256);
;     const half_t* urow = ub + (size_t)t * NU;
;     const int col = lane & 15;
;     h8 q0, q1;
; #pragma unroll
;     for (int e = 0; e < 8; ++e) { q0[e] = (half_t)0.f; q1[e] = (half_t)0.f; }
;     if (col < 8) {
;       q0 = *(const h8*)(urow + C_BQ + col * 64 + hq * 8);
;       q1 = *(const h8*)(urow + C_BQ + col * 64 + 32 + hq * 8);
;     }
;     float mx = NEGF;
; #pragma unroll 1
;     for (int mg = 0; mg < 2; ++mg) {
; #pragma unroll
;       for (int mm = 0; mm < 8; ++mm) {
;         const int m = mg * 8 + mm;
;         const int pos = m * 16 + col;
;         const int s = (pos < nsel) ? (int)sel[tk * 256 + pos] : 0;
;         const half_t* kp = ub + (size_t)s * NU + C_BK + hq * 8;
;         const h8 a0 = *(const h8*)kp, a1 = *(const h8*)(kp + 32);
.LBB0_1427:
	s_or_b64 exec, exec, s[2:3]
	s_waitcnt lgkmcnt(0)
	v_min_i32_e32 v85, 0x100, v11
	v_lshlrev_b32_e32 v14, 9, v10
	v_mov_b32_e32 v15, 0xf149f2ca
	s_add_u32 s14, s78, 0x3800
	s_addc_u32 s15, s79, 0
	v_add_u32_e32 v203, v126, v157
	v_lshl_add_u32 v80, v203, 1, v14
	ds_read_u16 v172, v80 offset:32768
	ds_read_u16 v173, v80 offset:32896
	ds_read_u16 v174, v80 offset:33024
	ds_read_u16 v175, v80 offset:33152
	v_and_b32_e32 v200, 7, v157
	v_lshlrev_b32_e32 v200, 4, v200
	v_mul_u32_u24_e32 v201, 0x240, v159
	v_add_u32_e32 v201, 0xa800, v201
	v_mul_u32_u24_e32 v198, 0x90, v165
	v_add3_u32 v198, v198, v200, v201
	v_mul_u32_u24_e32 v199, 0x90, v157
	v_add3_u32 v199, v199, v126, v201
	v_lshlrev_b32_e32 v202, 8, v159
	v_add_u32_e32 v202, 0xcc00, v202
	v_lshl_add_u32 v81, v203, 2, v202
	v_add_u32_e32 v171, -1, v85
	v_add_u32_e32 v156, -2, v85
	v_add_u32_e32 v158, -3, v85
	v_cmp_lt_i32_e32 vcc, v203, v85
	s_waitcnt lgkmcnt(3)
	s_nop 0
	v_cndmask_b32_e32 v172, 0, v172, vcc
	v_mul_u32_u24_e32 v172, 0x3a00, v172
	ds_write_b32 v81, v172
	v_add_u32_e32 v201, 64, v203
	v_cmp_lt_i32_e32 vcc, v201, v85
	s_waitcnt lgkmcnt(2)
	s_nop 0
	v_cndmask_b32_e32 v173, 0, v173, vcc
	v_mul_u32_u24_e32 v173, 0x3a00, v173
	ds_write_b32 v81, v173 offset:256
	v_add_u32_e32 v201, 0x80, v203
	v_cmp_lt_i32_e32 vcc, v201, v85
	s_waitcnt lgkmcnt(1)
	s_nop 0
	v_cndmask_b32_e32 v174, 0, v174, vcc
	v_mul_u32_u24_e32 v174, 0x3a00, v174
	ds_write_b32 v81, v174 offset:512
	v_add_u32_e32 v201, 0xc0, v203
	v_cmp_lt_i32_e32 vcc, v201, v85
	s_waitcnt lgkmcnt(0)
	s_nop 0
	v_cndmask_b32_e32 v175, 0, v175, vcc
	v_mul_u32_u24_e32 v175, 0x3a00, v175
	ds_write_b32 v81, v175 offset:768
	v_lshl_add_u32 v202, v165, 2, v202
	ds_read_b32 v172, v202
	ds_read_b32 v173, v202 offset:64
	ds_read_b32 v174, v202 offset:128
	ds_read_b32 v175, v202 offset:192
	ds_read_b32 v176, v202 offset:256
	ds_read_b32 v177, v202 offset:320
	ds_read_b32 v178, v202 offset:384
	ds_read_b32 v179, v202 offset:448
	ds_read_b32 v180, v202 offset:512
	ds_read_b32 v181, v202 offset:576
	ds_read_b32 v188, v202 offset:640
	ds_read_b32 v189, v202 offset:704
	ds_read_b32 v190, v202 offset:768
	ds_read_b32 v191, v202 offset:832
	ds_read_b32 v192, v202 offset:896
	ds_read_b32 v193, v202 offset:960
	s_waitcnt lgkmcnt(15)
	v_add_u32_e32 v172, v172, v200
	global_load_dwordx4 v[16:19], v172, s[14:15]
	s_waitcnt lgkmcnt(14)
	v_add_u32_e32 v173, v173, v200
	global_load_dwordx4 v[24:27], v173, s[14:15]
	s_waitcnt lgkmcnt(13)
	v_add_u32_e32 v174, v174, v200
	global_load_dwordx4 v[32:35], v174, s[14:15]
	s_waitcnt lgkmcnt(12)
	v_add_u32_e32 v175, v175, v200
	global_load_dwordx4 v[40:43], v175, s[14:15]
	s_waitcnt lgkmcnt(11)
	v_add_u32_e32 v176, v176, v200
	global_load_dwordx4 v[48:51], v176, s[14:15]
	s_waitcnt lgkmcnt(10)
	v_add_u32_e32 v177, v177, v200
	global_load_dwordx4 v[56:59], v177, s[14:15]
	s_waitcnt lgkmcnt(9)
	v_add_u32_e32 v178, v178, v200
	global_load_dwordx4 v[64:67], v178, s[14:15]
	s_waitcnt lgkmcnt(8)
	v_add_u32_e32 v179, v179, v200
	global_load_dwordx4 v[72:75], v179, s[14:15]
	s_waitcnt lgkmcnt(7)
	v_add_u32_e32 v180, v180, v200
	global_load_dwordx4 v[90:93], v180, s[14:15]
	s_waitcnt lgkmcnt(6)
	v_add_u32_e32 v181, v181, v200
	global_load_dwordx4 v[98:101], v181, s[14:15]
	s_waitcnt lgkmcnt(5)
	v_add_u32_e32 v188, v188, v200
	global_load_dwordx4 v[106:109], v188, s[14:15]
	s_waitcnt lgkmcnt(4)
	v_add_u32_e32 v189, v189, v200
	global_load_dwordx4 v[114:117], v189, s[14:15]
	s_waitcnt lgkmcnt(3)
	v_add_u32_e32 v190, v190, v200
	global_load_dwordx4 v[122:125], v190, s[14:15]
	s_waitcnt lgkmcnt(2)
	v_add_u32_e32 v191, v191, v200
	global_load_dwordx4 v[132:135], v191, s[14:15]
	s_waitcnt lgkmcnt(1)
	v_add_u32_e32 v192, v192, v200
	global_load_dwordx4 v[140:143], v192, s[14:15]
	s_waitcnt lgkmcnt(0)
	v_add_u32_e32 v193, v193, v200
	global_load_dwordx4 v[148:151], v193, s[14:15]
	ds_read_b32 v172, v202 offset:32
	ds_read_b32 v173, v202 offset:96
	ds_read_b32 v174, v202 offset:160
	ds_read_b32 v175, v202 offset:224
	ds_read_b32 v176, v202 offset:288
	ds_read_b32 v177, v202 offset:352
	ds_read_b32 v178, v202 offset:416
	ds_read_b32 v179, v202 offset:480
	ds_read_b32 v180, v202 offset:544
	ds_read_b32 v181, v202 offset:608
	ds_read_b32 v188, v202 offset:672
	ds_read_b32 v189, v202 offset:736
	ds_read_b32 v190, v202 offset:800
	ds_read_b32 v191, v202 offset:864
	ds_read_b32 v192, v202 offset:928
	ds_read_b32 v193, v202 offset:992
	s_waitcnt lgkmcnt(15)
	v_add_u32_e32 v172, v172, v200
	global_load_dwordx4 v[20:23], v172, s[14:15]
	s_waitcnt lgkmcnt(14)
	v_add_u32_e32 v173, v173, v200
	global_load_dwordx4 v[28:31], v173, s[14:15]
	s_waitcnt lgkmcnt(13)
	v_add_u32_e32 v174, v174, v200
	global_load_dwordx4 v[36:39], v174, s[14:15]
	s_waitcnt lgkmcnt(12)
	v_add_u32_e32 v175, v175, v200
	global_load_dwordx4 v[44:47], v175, s[14:15]
	s_waitcnt lgkmcnt(11)
	v_add_u32_e32 v176, v176, v200
	global_load_dwordx4 v[52:55], v176, s[14:15]
	s_waitcnt lgkmcnt(10)
	v_add_u32_e32 v177, v177, v200
	global_load_dwordx4 v[60:63], v177, s[14:15]
	s_waitcnt lgkmcnt(9)
	v_add_u32_e32 v178, v178, v200
	global_load_dwordx4 v[68:71], v178, s[14:15]
	s_waitcnt lgkmcnt(8)
	v_add_u32_e32 v179, v179, v200
	global_load_dwordx4 v[76:79], v179, s[14:15]
	s_waitcnt lgkmcnt(7)
	v_add_u32_e32 v180, v180, v200
	global_load_dwordx4 v[94:97], v180, s[14:15]
	s_waitcnt lgkmcnt(6)
	v_add_u32_e32 v181, v181, v200
	global_load_dwordx4 v[102:105], v181, s[14:15]
	s_waitcnt lgkmcnt(5)
	v_add_u32_e32 v188, v188, v200
	global_load_dwordx4 v[110:113], v188, s[14:15]
	s_waitcnt lgkmcnt(4)
	v_add_u32_e32 v189, v189, v200
	global_load_dwordx4 v[118:121], v189, s[14:15]
	s_waitcnt lgkmcnt(3)
	v_add_u32_e32 v190, v190, v200
	global_load_dwordx4 v[128:131], v190, s[14:15]
	s_waitcnt lgkmcnt(2)
	v_add_u32_e32 v191, v191, v200
	global_load_dwordx4 v[136:139], v191, s[14:15]
	s_waitcnt lgkmcnt(1)
	v_add_u32_e32 v192, v192, v200
	global_load_dwordx4 v[144:147], v192, s[14:15]
	s_waitcnt lgkmcnt(0)
	v_add_u32_e32 v193, v193, v200
	global_load_dwordx4 v[152:155], v193, s[14:15]
	v_readfirstlane_b32 s2, v85
	s_nop 1
	s_cmp_eq_u32 s2, 0x100
	s_cbranch_scc1 .Lqk_full
;   __device__ __forceinline__ half_t* mm() const { return (half_t*)(ws() + OFF_mm); }
; __device__ __forceinline__ void dsa_item(const KP& p, int b, int tile, char* smem) {
;     ...
;       for (int mm = 0; mm < 8; ++mm) {
;         const int m = mg * 8 + mm;
;         const int pos = m * 16 + col;
;         const int s = (pos < nsel) ? (int)sel[tk * 256 + pos] : 0;
;         const half_t* kp = ub + (size_t)s * NU + C_BK + hq * 8;
;         const h8 a0 = *(const h8*)kp, a1 = *(const h8*)(kp + 32);
;         f32x4 d = {0.f, 0.f, 0.f, 0.f};
;         d = __builtin_amdgcn_mfma_f32_16x16x32_f16(a0, q0, d, 0, 0, 0);
;         d = __builtin_amdgcn_mfma_f32_16x16x32_f16(a1, q1, d, 0, 0, 0);
; #pragma unroll
;         for (int r = 0; r < 4; ++r) {
;           const int pp = m * 16 + hq * 4 + r;
;           const float v = (pp < nsel) ? d[r] * 0.125f : NEGF;
;           mx = fmaxf(mx, v);
;           if (col < 8) pbuf[pp * 8 + col] = v;
;         }
	s_waitcnt vmcnt(15)
	ds_write_b128 v198, v[16:19]
	ds_write_b128 v198, v[20:23] offset:1152
	ds_read_b128 v[16:19], v199
	ds_read_b128 v[20:23], v199 offset:64
	s_waitcnt vmcnt(14)
	ds_write_b128 v198, v[24:27]
	ds_write_b128 v198, v[28:31] offset:1152
	ds_read_b128 v[24:27], v199
	ds_read_b128 v[28:31], v199 offset:64
	s_waitcnt lgkmcnt(4)
	v_mfma_f32_16x16x32_f16 v[10:13], v[16:19], v[6:9], 0
	v_mfma_f32_16x16x32_f16 v[10:13], v[20:23], v[2:5], v[10:13]
	s_nop 4
	s_waitcnt vmcnt(13)
	ds_write_b128 v198, v[32:35]
	ds_write_b128 v198, v[36:39] offset:1152
	ds_read_b128 v[32:35], v199
	ds_read_b128 v[36:39], v199 offset:64
	s_waitcnt lgkmcnt(4)
	v_mfma_f32_16x16x32_f16 v[194:197], v[24:27], v[6:9], 0
	v_mfma_f32_16x16x32_f16 v[194:197], v[28:31], v[2:5], v[194:197]
	v_or_b32_e32 v80, 0, v160
	v_mul_f32_e32 v10, 0x3e000000, v10
	v_mul_f32_e32 v11, 0x3e000000, v11
	v_mul_f32_e32 v12, 0x3e000000, v12
	v_mul_f32_e32 v13, 0x3e000000, v13
	v_cmp_lt_i32_e32 vcc, v80, v85
	v_cmp_lt_i32_e64 s[46:47], v80, v171
	v_lshl_add_u32 v81, v80, 5, v167
	s_nop 0
	v_cndmask_b32_e32 v10, v242, v10, vcc
	v_cndmask_b32_e64 v11, v242, v11, s[46:47]
	v_cmp_lt_i32_e32 vcc, v80, v156
	v_cmp_lt_i32_e64 s[46:47], v80, v158
	v_max3_f32 v15, v15, v10, v11
	s_nop 0
	v_cndmask_b32_e32 v12, v242, v12, vcc
	v_cndmask_b32_e64 v13, v242, v13, s[46:47]
	v_max3_f32 v15, v15, v12, v13
	s_and_saveexec_b64 s[2:3], s[38:39]
	ds_write_b32 v81, v10
	ds_write_b32 v81, v11 offset:32
	ds_write_b32 v81, v12 offset:64
	ds_write_b32 v81, v13 offset:96
	s_or_b64 exec, exec, s[2:3]
	s_waitcnt vmcnt(12)
	ds_write_b128 v198, v[40:43]
	ds_write_b128 v198, v[44:47] offset:1152
	ds_read_b128 v[40:43], v199
	ds_read_b128 v[44:47], v199 offset:64
	s_waitcnt lgkmcnt(8)
	v_mfma_f32_16x16x32_f16 v[10:13], v[32:35], v[6:9], 0
	v_mfma_f32_16x16x32_f16 v[10:13], v[36:39], v[2:5], v[10:13]
	v_or_b32_e32 v80, 16, v160
	v_mul_f32_e32 v194, 0x3e000000, v194
	v_mul_f32_e32 v195, 0x3e000000, v195
	v_mul_f32_e32 v196, 0x3e000000, v196
	v_mul_f32_e32 v197, 0x3e000000, v197
	v_cmp_lt_i32_e32 vcc, v80, v85
	v_cmp_lt_i32_e64 s[46:47], v80, v171
	v_lshl_add_u32 v81, v80, 5, v167
	s_nop 0
	v_cndmask_b32_e32 v194, v242, v194, vcc
	v_cndmask_b32_e64 v195, v242, v195, s[46:47]
	v_cmp_lt_i32_e32 vcc, v80, v156
	v_cmp_lt_i32_e64 s[46:47], v80, v158
	v_max3_f32 v15, v15, v194, v195
	s_nop 0
	v_cndmask_b32_e32 v196, v242, v196, vcc
	v_cndmask_b32_e64 v197, v242, v197, s[46:47]
	v_max3_f32 v15, v15, v196, v197
	s_and_saveexec_b64 s[2:3], s[38:39]
	ds_write_b32 v81, v194
	ds_write_b32 v81, v195 offset:32
	ds_write_b32 v81, v196 offset:64
	ds_write_b32 v81, v197 offset:96
	s_or_b64 exec, exec, s[2:3]
	s_waitcnt vmcnt(11)
	ds_write_b128 v198, v[48:51]
	ds_write_b128 v198, v[52:55] offset:1152
	ds_read_b128 v[48:51], v199
	ds_read_b128 v[52:55], v199 offset:64
	s_waitcnt lgkmcnt(8)
	v_mfma_f32_16x16x32_f16 v[194:197], v[40:43], v[6:9], 0
	v_mfma_f32_16x16x32_f16 v[194:197], v[44:47], v[2:5], v[194:197]
	v_or_b32_e32 v80, 32, v160
	v_mul_f32_e32 v10, 0x3e000000, v10
	v_mul_f32_e32 v11, 0x3e000000, v11
	v_mul_f32_e32 v12, 0x3e000000, v12
	v_mul_f32_e32 v13, 0x3e000000, v13
	v_cmp_lt_i32_e32 vcc, v80, v85
	v_cmp_lt_i32_e64 s[46:47], v80, v171
	v_lshl_add_u32 v81, v80, 5, v167
	s_nop 0
	v_cndmask_b32_e32 v10, v242, v10, vcc
	v_cndmask_b32_e64 v11, v242, v11, s[46:47]
	v_cmp_lt_i32_e32 vcc, v80, v156
	v_cmp_lt_i32_e64 s[46:47], v80, v158
	v_max3_f32 v15, v15, v10, v11
	s_nop 0
	v_cndmask_b32_e32 v12, v242, v12, vcc
	v_cndmask_b32_e64 v13, v242, v13, s[46:47]
	v_max3_f32 v15, v15, v12, v13
	s_and_saveexec_b64 s[2:3], s[38:39]
	ds_write_b32 v81, v10
	ds_write_b32 v81, v11 offset:32
	ds_write_b32 v81, v12 offset:64
	ds_write_b32 v81, v13 offset:96
	s_or_b64 exec, exec, s[2:3]
	s_waitcnt vmcnt(10)
	ds_write_b128 v198, v[56:59]
	ds_write_b128 v198, v[60:63] offset:1152
	ds_read_b128 v[56:59], v199
	ds_read_b128 v[60:63], v199 offset:64
	s_waitcnt lgkmcnt(8)
	v_mfma_f32_16x16x32_f16 v[10:13], v[48:51], v[6:9], 0
	v_mfma_f32_16x16x32_f16 v[10:13], v[52:55], v[2:5], v[10:13]
	v_or_b32_e32 v80, 48, v160
	v_mul_f32_e32 v194, 0x3e000000, v194
	v_mul_f32_e32 v195, 0x3e000000, v195
	v_mul_f32_e32 v196, 0x3e000000, v196
	v_mul_f32_e32 v197, 0x3e000000, v197
	v_cmp_lt_i32_e32 vcc, v80, v85
	v_cmp_lt_i32_e64 s[46:47], v80, v171
	v_lshl_add_u32 v81, v80, 5, v167
	s_nop 0
	v_cndmask_b32_e32 v194, v242, v194, vcc
	v_cndmask_b32_e64 v195, v242, v195, s[46:47]
	v_cmp_lt_i32_e32 vcc, v80, v156
	v_cmp_lt_i32_e64 s[46:47], v80, v158
	v_max3_f32 v15, v15, v194, v195
	s_nop 0
	v_cndmask_b32_e32 v196, v242, v196, vcc
	v_cndmask_b32_e64 v197, v242, v197, s[46:47]
	v_max3_f32 v15, v15, v196, v197
	s_and_saveexec_b64 s[2:3], s[38:39]
	ds_write_b32 v81, v194
	ds_write_b32 v81, v195 offset:32
	ds_write_b32 v81, v196 offset:64
	ds_write_b32 v81, v197 offset:96
	s_or_b64 exec, exec, s[2:3]
	s_waitcnt vmcnt(9)
	ds_write_b128 v198, v[64:67]
	ds_write_b128 v198, v[68:71] offset:1152
	ds_read_b128 v[64:67], v199
	ds_read_b128 v[68:71], v199 offset:64
	s_waitcnt lgkmcnt(8)
	v_mfma_f32_16x16x32_f16 v[194:197], v[56:59], v[6:9], 0
	v_mfma_f32_16x16x32_f16 v[194:197], v[60:63], v[2:5], v[194:197]
	v_or_b32_e32 v80, 64, v160
	v_mul_f32_e32 v10, 0x3e000000, v10
	v_mul_f32_e32 v11, 0x3e000000, v11
	v_mul_f32_e32 v12, 0x3e000000, v12
	v_mul_f32_e32 v13, 0x3e000000, v13
	v_cmp_lt_i32_e32 vcc, v80, v85
	v_cmp_lt_i32_e64 s[46:47], v80, v171
	v_lshl_add_u32 v81, v80, 5, v167
	s_nop 0
	v_cndmask_b32_e32 v10, v242, v10, vcc
	v_cndmask_b32_e64 v11, v242, v11, s[46:47]
	v_cmp_lt_i32_e32 vcc, v80, v156
	v_cmp_lt_i32_e64 s[46:47], v80, v158
	v_max3_f32 v15, v15, v10, v11
	s_nop 0
	v_cndmask_b32_e32 v12, v242, v12, vcc
	v_cndmask_b32_e64 v13, v242, v13, s[46:47]
	v_max3_f32 v15, v15, v12, v13
	s_and_saveexec_b64 s[2:3], s[38:39]
	ds_write_b32 v81, v10
	ds_write_b32 v81, v11 offset:32
	ds_write_b32 v81, v12 offset:64
	ds_write_b32 v81, v13 offset:96
	s_or_b64 exec, exec, s[2:3]
	s_waitcnt vmcnt(8)
;   __device__ __forceinline__ half_t* mm() const { return (half_t*)(ws() + OFF_mm); }
; __device__ __forceinline__ void dsa_item(const KP& p, int b, int tile, char* smem) {
;     ...
;       for (int mm = 0; mm < 8; ++mm) {
;         const int m = mg * 8 + mm;
;         const int pos = m * 16 + col;
;         const int s = (pos < nsel) ? (int)sel[tk * 256 + pos] : 0;
;         const half_t* kp = ub + (size_t)s * NU + C_BK + hq * 8;
;         const h8 a0 = *(const h8*)kp, a1 = *(const h8*)(kp + 32);
;         f32x4 d = {0.f, 0.f, 0.f, 0.f};
;         d = __builtin_amdgcn_mfma_f32_16x16x32_f16(a0, q0, d, 0, 0, 0);
;         d = __builtin_amdgcn_mfma_f32_16x16x32_f16(a1, q1, d, 0, 0, 0);
; #pragma unroll
;         for (int r = 0; r < 4; ++r) {
;           const int pp = m * 16 + hq * 4 + r;
;           const float v = (pp < nsel) ? d[r] * 0.125f : NEGF;
;           mx = fmaxf(mx, v);
;           if (col < 8) pbuf[pp * 8 + col] = v;
;         }
	ds_write_b128 v198, v[72:75]
	ds_write_b128 v198, v[76:79] offset:1152
	ds_read_b128 v[72:75], v199
	ds_read_b128 v[76:79], v199 offset:64
	s_waitcnt lgkmcnt(8)
	v_mfma_f32_16x16x32_f16 v[10:13], v[64:67], v[6:9], 0
	v_mfma_f32_16x16x32_f16 v[10:13], v[68:71], v[2:5], v[10:13]
	v_or_b32_e32 v80, 0x50, v160
	v_mul_f32_e32 v194, 0x3e000000, v194
	v_mul_f32_e32 v195, 0x3e000000, v195
	v_mul_f32_e32 v196, 0x3e000000, v196
	v_mul_f32_e32 v197, 0x3e000000, v197
	v_cmp_lt_i32_e32 vcc, v80, v85
	v_cmp_lt_i32_e64 s[46:47], v80, v171
	v_lshl_add_u32 v81, v80, 5, v167
	s_nop 0
	v_cndmask_b32_e32 v194, v242, v194, vcc
	v_cndmask_b32_e64 v195, v242, v195, s[46:47]
	v_cmp_lt_i32_e32 vcc, v80, v156
	v_cmp_lt_i32_e64 s[46:47], v80, v158
	v_max3_f32 v15, v15, v194, v195
	s_nop 0
	v_cndmask_b32_e32 v196, v242, v196, vcc
	v_cndmask_b32_e64 v197, v242, v197, s[46:47]
	v_max3_f32 v15, v15, v196, v197
	s_and_saveexec_b64 s[2:3], s[38:39]
	ds_write_b32 v81, v194
	ds_write_b32 v81, v195 offset:32
	ds_write_b32 v81, v196 offset:64
	ds_write_b32 v81, v197 offset:96
	s_or_b64 exec, exec, s[2:3]
	s_waitcnt vmcnt(7)
	ds_write_b128 v198, v[90:93]
	ds_write_b128 v198, v[94:97] offset:1152
	ds_read_b128 v[90:93], v199
	ds_read_b128 v[94:97], v199 offset:64
	s_waitcnt lgkmcnt(8)
	v_mfma_f32_16x16x32_f16 v[194:197], v[72:75], v[6:9], 0
	v_mfma_f32_16x16x32_f16 v[194:197], v[76:79], v[2:5], v[194:197]
	v_or_b32_e32 v80, 0x60, v160
	v_mul_f32_e32 v10, 0x3e000000, v10
	v_mul_f32_e32 v11, 0x3e000000, v11
	v_mul_f32_e32 v12, 0x3e000000, v12
	v_mul_f32_e32 v13, 0x3e000000, v13
	v_cmp_lt_i32_e32 vcc, v80, v85
	v_cmp_lt_i32_e64 s[46:47], v80, v171
	v_lshl_add_u32 v81, v80, 5, v167
	s_nop 0
	v_cndmask_b32_e32 v10, v242, v10, vcc
	v_cndmask_b32_e64 v11, v242, v11, s[46:47]
	v_cmp_lt_i32_e32 vcc, v80, v156
	v_cmp_lt_i32_e64 s[46:47], v80, v158
	v_max3_f32 v15, v15, v10, v11
	s_nop 0
	v_cndmask_b32_e32 v12, v242, v12, vcc
	v_cndmask_b32_e64 v13, v242, v13, s[46:47]
	v_max3_f32 v15, v15, v12, v13
	s_and_saveexec_b64 s[2:3], s[38:39]
	ds_write_b32 v81, v10
	ds_write_b32 v81, v11 offset:32
	ds_write_b32 v81, v12 offset:64
	ds_write_b32 v81, v13 offset:96
	s_or_b64 exec, exec, s[2:3]
	s_waitcnt vmcnt(6)
	ds_write_b128 v198, v[98:101]
	ds_write_b128 v198, v[102:105] offset:1152
	ds_read_b128 v[98:101], v199
	ds_read_b128 v[102:105], v199 offset:64
	s_waitcnt lgkmcnt(8)
	v_mfma_f32_16x16x32_f16 v[10:13], v[90:93], v[6:9], 0
	v_mfma_f32_16x16x32_f16 v[10:13], v[94:97], v[2:5], v[10:13]
	v_or_b32_e32 v80, 0x70, v160
	v_mul_f32_e32 v194, 0x3e000000, v194
	v_mul_f32_e32 v195, 0x3e000000, v195
	v_mul_f32_e32 v196, 0x3e000000, v196
	v_mul_f32_e32 v197, 0x3e000000, v197
	v_cmp_lt_i32_e32 vcc, v80, v85
	v_cmp_lt_i32_e64 s[46:47], v80, v171
	v_lshl_add_u32 v81, v80, 5, v167
	s_nop 0
	v_cndmask_b32_e32 v194, v242, v194, vcc
	v_cndmask_b32_e64 v195, v242, v195, s[46:47]
	v_cmp_lt_i32_e32 vcc, v80, v156
	v_cmp_lt_i32_e64 s[46:47], v80, v158
	v_max3_f32 v15, v15, v194, v195
	s_nop 0
	v_cndmask_b32_e32 v196, v242, v196, vcc
	v_cndmask_b32_e64 v197, v242, v197, s[46:47]
	v_max3_f32 v15, v15, v196, v197
	s_and_saveexec_b64 s[2:3], s[38:39]
	ds_write_b32 v81, v194
	ds_write_b32 v81, v195 offset:32
	ds_write_b32 v81, v196 offset:64
	ds_write_b32 v81, v197 offset:96
	s_or_b64 exec, exec, s[2:3]
	s_waitcnt vmcnt(5)
	ds_write_b128 v198, v[106:109]
	ds_write_b128 v198, v[110:113] offset:1152
	ds_read_b128 v[106:109], v199
	ds_read_b128 v[110:113], v199 offset:64
	s_waitcnt lgkmcnt(8)
	v_mfma_f32_16x16x32_f16 v[194:197], v[98:101], v[6:9], 0
	v_mfma_f32_16x16x32_f16 v[194:197], v[102:105], v[2:5], v[194:197]
	v_or_b32_e32 v80, 0x80, v160
	v_mul_f32_e32 v10, 0x3e000000, v10
	v_mul_f32_e32 v11, 0x3e000000, v11
	v_mul_f32_e32 v12, 0x3e000000, v12
	v_mul_f32_e32 v13, 0x3e000000, v13
	v_cmp_lt_i32_e32 vcc, v80, v85
	v_cmp_lt_i32_e64 s[46:47], v80, v171
	v_lshl_add_u32 v81, v80, 5, v167
	s_nop 0
	v_cndmask_b32_e32 v10, v242, v10, vcc
	v_cndmask_b32_e64 v11, v242, v11, s[46:47]
	v_cmp_lt_i32_e32 vcc, v80, v156
	v_cmp_lt_i32_e64 s[46:47], v80, v158
	v_max3_f32 v15, v15, v10, v11
	s_nop 0
	v_cndmask_b32_e32 v12, v242, v12, vcc
	v_cndmask_b32_e64 v13, v242, v13, s[46:47]
	v_max3_f32 v15, v15, v12, v13
	s_and_saveexec_b64 s[2:3], s[38:39]
	ds_write_b32 v81, v10
	ds_write_b32 v81, v11 offset:32
	ds_write_b32 v81, v12 offset:64
	ds_write_b32 v81, v13 offset:96
	s_or_b64 exec, exec, s[2:3]
	s_waitcnt vmcnt(4)
	ds_write_b128 v198, v[114:117]
	ds_write_b128 v198, v[118:121] offset:1152
	ds_read_b128 v[114:117], v199
	ds_read_b128 v[118:121], v199 offset:64
	s_waitcnt lgkmcnt(8)
	v_mfma_f32_16x16x32_f16 v[10:13], v[106:109], v[6:9], 0
	v_mfma_f32_16x16x32_f16 v[10:13], v[110:113], v[2:5], v[10:13]
	v_or_b32_e32 v80, 0x90, v160
	v_mul_f32_e32 v194, 0x3e000000, v194
	v_mul_f32_e32 v195, 0x3e000000, v195
	v_mul_f32_e32 v196, 0x3e000000, v196
	v_mul_f32_e32 v197, 0x3e000000, v197
	v_cmp_lt_i32_e32 vcc, v80, v85
	v_cmp_lt_i32_e64 s[46:47], v80, v171
	v_lshl_add_u32 v81, v80, 5, v167
	s_nop 0
	v_cndmask_b32_e32 v194, v242, v194, vcc
	v_cndmask_b32_e64 v195, v242, v195, s[46:47]
	v_cmp_lt_i32_e32 vcc, v80, v156
	v_cmp_lt_i32_e64 s[46:47], v80, v158
	v_max3_f32 v15, v15, v194, v195
	s_nop 0
	v_cndmask_b32_e32 v196, v242, v196, vcc
	v_cndmask_b32_e64 v197, v242, v197, s[46:47]
	v_max3_f32 v15, v15, v196, v197
	s_and_saveexec_b64 s[2:3], s[38:39]
	ds_write_b32 v81, v194
	ds_write_b32 v81, v195 offset:32
	ds_write_b32 v81, v196 offset:64
	ds_write_b32 v81, v197 offset:96
	s_or_b64 exec, exec, s[2:3]
	s_waitcnt vmcnt(3)
	ds_write_b128 v198, v[122:125]
	ds_write_b128 v198, v[128:131] offset:1152
	ds_read_b128 v[122:125], v199
	ds_read_b128 v[128:131], v199 offset:64
	s_waitcnt lgkmcnt(8)
;   __device__ __forceinline__ half_t* mm() const { return (half_t*)(ws() + OFF_mm); }
; __device__ __forceinline__ void dsa_item(const KP& p, int b, int tile, char* smem) {
;     ...
;       for (int mm = 0; mm < 8; ++mm) {
;         const int m = mg * 8 + mm;
;         const int pos = m * 16 + col;
;         const int s = (pos < nsel) ? (int)sel[tk * 256 + pos] : 0;
;         const half_t* kp = ub + (size_t)s * NU + C_BK + hq * 8;
;         const h8 a0 = *(const h8*)kp, a1 = *(const h8*)(kp + 32);
;         f32x4 d = {0.f, 0.f, 0.f, 0.f};
;         d = __builtin_amdgcn_mfma_f32_16x16x32_f16(a0, q0, d, 0, 0, 0);
;         d = __builtin_amdgcn_mfma_f32_16x16x32_f16(a1, q1, d, 0, 0, 0);
; #pragma unroll
;         for (int r = 0; r < 4; ++r) {
;           const int pp = m * 16 + hq * 4 + r;
;           const float v = (pp < nsel) ? d[r] * 0.125f : NEGF;
;           mx = fmaxf(mx, v);
;           if (col < 8) pbuf[pp * 8 + col] = v;
;         }
	v_mfma_f32_16x16x32_f16 v[194:197], v[114:117], v[6:9], 0
	v_mfma_f32_16x16x32_f16 v[194:197], v[118:121], v[2:5], v[194:197]
	v_or_b32_e32 v80, 0xa0, v160
	v_mul_f32_e32 v10, 0x3e000000, v10
	v_mul_f32_e32 v11, 0x3e000000, v11
	v_mul_f32_e32 v12, 0x3e000000, v12
	v_mul_f32_e32 v13, 0x3e000000, v13
	v_cmp_lt_i32_e32 vcc, v80, v85
	v_cmp_lt_i32_e64 s[46:47], v80, v171
	v_lshl_add_u32 v81, v80, 5, v167
	s_nop 0
	v_cndmask_b32_e32 v10, v242, v10, vcc
	v_cndmask_b32_e64 v11, v242, v11, s[46:47]
	v_cmp_lt_i32_e32 vcc, v80, v156
	v_cmp_lt_i32_e64 s[46:47], v80, v158
	v_max3_f32 v15, v15, v10, v11
	s_nop 0
	v_cndmask_b32_e32 v12, v242, v12, vcc
	v_cndmask_b32_e64 v13, v242, v13, s[46:47]
	v_max3_f32 v15, v15, v12, v13
	s_and_saveexec_b64 s[2:3], s[38:39]
	ds_write_b32 v81, v10
	ds_write_b32 v81, v11 offset:32
	ds_write_b32 v81, v12 offset:64
	ds_write_b32 v81, v13 offset:96
	s_or_b64 exec, exec, s[2:3]
	s_waitcnt vmcnt(2)
	ds_write_b128 v198, v[132:135]
	ds_write_b128 v198, v[136:139] offset:1152
	ds_read_b128 v[132:135], v199
	ds_read_b128 v[136:139], v199 offset:64
	s_waitcnt lgkmcnt(8)
	v_mfma_f32_16x16x32_f16 v[10:13], v[122:125], v[6:9], 0
	v_mfma_f32_16x16x32_f16 v[10:13], v[128:131], v[2:5], v[10:13]
	v_or_b32_e32 v80, 0xb0, v160
	v_mul_f32_e32 v194, 0x3e000000, v194
	v_mul_f32_e32 v195, 0x3e000000, v195
	v_mul_f32_e32 v196, 0x3e000000, v196
	v_mul_f32_e32 v197, 0x3e000000, v197
	v_cmp_lt_i32_e32 vcc, v80, v85
	v_cmp_lt_i32_e64 s[46:47], v80, v171
	v_lshl_add_u32 v81, v80, 5, v167
	s_nop 0
	v_cndmask_b32_e32 v194, v242, v194, vcc
	v_cndmask_b32_e64 v195, v242, v195, s[46:47]
	v_cmp_lt_i32_e32 vcc, v80, v156
	v_cmp_lt_i32_e64 s[46:47], v80, v158
	v_max3_f32 v15, v15, v194, v195
	s_nop 0
	v_cndmask_b32_e32 v196, v242, v196, vcc
	v_cndmask_b32_e64 v197, v242, v197, s[46:47]
	v_max3_f32 v15, v15, v196, v197
	s_and_saveexec_b64 s[2:3], s[38:39]
	ds_write_b32 v81, v194
	ds_write_b32 v81, v195 offset:32
	ds_write_b32 v81, v196 offset:64
	ds_write_b32 v81, v197 offset:96
	s_or_b64 exec, exec, s[2:3]
	s_waitcnt vmcnt(1)
	ds_write_b128 v198, v[140:143]
	ds_write_b128 v198, v[144:147] offset:1152
	ds_read_b128 v[140:143], v199
	ds_read_b128 v[144:147], v199 offset:64
	s_waitcnt lgkmcnt(8)
	v_mfma_f32_16x16x32_f16 v[194:197], v[132:135], v[6:9], 0
	v_mfma_f32_16x16x32_f16 v[194:197], v[136:139], v[2:5], v[194:197]
	v_or_b32_e32 v80, 0xc0, v160
	v_mul_f32_e32 v10, 0x3e000000, v10
	v_mul_f32_e32 v11, 0x3e000000, v11
	v_mul_f32_e32 v12, 0x3e000000, v12
	v_mul_f32_e32 v13, 0x3e000000, v13
	v_cmp_lt_i32_e32 vcc, v80, v85
	v_cmp_lt_i32_e64 s[46:47], v80, v171
	v_lshl_add_u32 v81, v80, 5, v167
	s_nop 0
	v_cndmask_b32_e32 v10, v242, v10, vcc
	v_cndmask_b32_e64 v11, v242, v11, s[46:47]
	v_cmp_lt_i32_e32 vcc, v80, v156
	v_cmp_lt_i32_e64 s[46:47], v80, v158
	v_max3_f32 v15, v15, v10, v11
	s_nop 0
	v_cndmask_b32_e32 v12, v242, v12, vcc
	v_cndmask_b32_e64 v13, v242, v13, s[46:47]
	v_max3_f32 v15, v15, v12, v13
	s_and_saveexec_b64 s[2:3], s[38:39]
	ds_write_b32 v81, v10
	ds_write_b32 v81, v11 offset:32
	ds_write_b32 v81, v12 offset:64
	ds_write_b32 v81, v13 offset:96
	s_or_b64 exec, exec, s[2:3]
	s_waitcnt vmcnt(0)
	ds_write_b128 v198, v[148:151]
	ds_write_b128 v198, v[152:155] offset:1152
	ds_read_b128 v[148:151], v199
	ds_read_b128 v[152:155], v199 offset:64
	s_waitcnt lgkmcnt(8)
	v_mfma_f32_16x16x32_f16 v[10:13], v[140:143], v[6:9], 0
	v_mfma_f32_16x16x32_f16 v[10:13], v[144:147], v[2:5], v[10:13]
	v_or_b32_e32 v80, 0xd0, v160
	v_mul_f32_e32 v194, 0x3e000000, v194
	v_mul_f32_e32 v195, 0x3e000000, v195
	v_mul_f32_e32 v196, 0x3e000000, v196
	v_mul_f32_e32 v197, 0x3e000000, v197
	v_cmp_lt_i32_e32 vcc, v80, v85
	v_cmp_lt_i32_e64 s[46:47], v80, v171
	v_lshl_add_u32 v81, v80, 5, v167
	s_nop 0
	v_cndmask_b32_e32 v194, v242, v194, vcc
	v_cndmask_b32_e64 v195, v242, v195, s[46:47]
	v_cmp_lt_i32_e32 vcc, v80, v156
	v_cmp_lt_i32_e64 s[46:47], v80, v158
	v_max3_f32 v15, v15, v194, v195
	s_nop 0
	v_cndmask_b32_e32 v196, v242, v196, vcc
	v_cndmask_b32_e64 v197, v242, v197, s[46:47]
	v_max3_f32 v15, v15, v196, v197
	s_and_saveexec_b64 s[2:3], s[38:39]
	ds_write_b32 v81, v194
	ds_write_b32 v81, v195 offset:32
	ds_write_b32 v81, v196 offset:64
	ds_write_b32 v81, v197 offset:96
	s_or_b64 exec, exec, s[2:3]
	s_waitcnt lgkmcnt(4)
	v_mfma_f32_16x16x32_f16 v[194:197], v[148:151], v[6:9], 0
	v_mfma_f32_16x16x32_f16 v[194:197], v[152:155], v[2:5], v[194:197]
	v_or_b32_e32 v80, 0xe0, v160
	v_mul_f32_e32 v10, 0x3e000000, v10
	v_mul_f32_e32 v11, 0x3e000000, v11
	v_mul_f32_e32 v12, 0x3e000000, v12
	v_mul_f32_e32 v13, 0x3e000000, v13
	v_cmp_lt_i32_e32 vcc, v80, v85
	v_cmp_lt_i32_e64 s[46:47], v80, v171
	v_lshl_add_u32 v81, v80, 5, v167
	s_nop 0
	v_cndmask_b32_e32 v10, v242, v10, vcc
	v_cndmask_b32_e64 v11, v242, v11, s[46:47]
	v_cmp_lt_i32_e32 vcc, v80, v156
	v_cmp_lt_i32_e64 s[46:47], v80, v158
	v_max3_f32 v15, v15, v10, v11
	s_nop 0
	v_cndmask_b32_e32 v12, v242, v12, vcc
	v_cndmask_b32_e64 v13, v242, v13, s[46:47]
	v_max3_f32 v15, v15, v12, v13
	s_and_saveexec_b64 s[2:3], s[38:39]
	ds_write_b32 v81, v10
	ds_write_b32 v81, v11 offset:32
	ds_write_b32 v81, v12 offset:64
	ds_write_b32 v81, v13 offset:96
	s_or_b64 exec, exec, s[2:3]
	s_nop 7
	v_or_b32_e32 v80, 0xf0, v160
	v_mul_f32_e32 v194, 0x3e000000, v194
	v_mul_f32_e32 v195, 0x3e000000, v195
	v_mul_f32_e32 v196, 0x3e000000, v196
	v_mul_f32_e32 v197, 0x3e000000, v197
	v_cmp_lt_i32_e32 vcc, v80, v85
	v_cmp_lt_i32_e64 s[46:47], v80, v171
	v_lshl_add_u32 v81, v80, 5, v167
	s_nop 0
	v_cndmask_b32_e32 v194, v242, v194, vcc
	v_cndmask_b32_e64 v195, v242, v195, s[46:47]
	v_cmp_lt_i32_e32 vcc, v80, v156
	v_cmp_lt_i32_e64 s[46:47], v80, v158
	v_max3_f32 v15, v15, v194, v195
	s_nop 0
	v_cndmask_b32_e32 v196, v242, v196, vcc
	v_cndmask_b32_e64 v197, v242, v197, s[46:47]
	v_max3_f32 v15, v15, v196, v197
	s_and_saveexec_b64 s[2:3], s[38:39]
	ds_write_b32 v81, v194
	ds_write_b32 v81, v195 offset:32
	ds_write_b32 v81, v196 offset:64
	ds_write_b32 v81, v197 offset:96
	s_or_b64 exec, exec, s[2:3]
	s_branch .LBB0_1509
;   __device__ __forceinline__ half_t* mm() const { return (half_t*)(ws() + OFF_mm); }
; __device__ __forceinline__ void dsa_item(const KP& p, int b, int tile, char* smem) {
;     ...
;       for (int mm = 0; mm < 8; ++mm) {
;         const int m = mg * 8 + mm;
;         const int pos = m * 16 + col;
;         const int s = (pos < nsel) ? (int)sel[tk * 256 + pos] : 0;
;         const half_t* kp = ub + (size_t)s * NU + C_BK + hq * 8;
;         const h8 a0 = *(const h8*)kp, a1 = *(const h8*)(kp + 32);
;         f32x4 d = {0.f, 0.f, 0.f, 0.f};
;         d = __builtin_amdgcn_mfma_f32_16x16x32_f16(a0, q0, d, 0, 0, 0);
;         d = __builtin_amdgcn_mfma_f32_16x16x32_f16(a1, q1, d, 0, 0, 0);
; #pragma unroll
;         for (int r = 0; r < 4; ++r) {
;           const int pp = m * 16 + hq * 4 + r;
;           const float v = (pp < nsel) ? d[r] * 0.125f : NEGF;
;           mx = fmaxf(mx, v);
;           if (col < 8) pbuf[pp * 8 + col] = v;
;         }
.Lqk_full:
	s_waitcnt vmcnt(15)
	ds_write_b128 v198, v[16:19]
	ds_write_b128 v198, v[20:23] offset:1152
	ds_read_b128 v[16:19], v199
	ds_read_b128 v[20:23], v199 offset:64
	s_waitcnt vmcnt(14)
	ds_write_b128 v198, v[24:27]
	ds_write_b128 v198, v[28:31] offset:1152
	ds_read_b128 v[24:27], v199
	ds_read_b128 v[28:31], v199 offset:64
	s_waitcnt lgkmcnt(4)
	v_mfma_f32_16x16x32_f16 v[10:13], v[16:19], v[6:9], 0
	v_mfma_f32_16x16x32_f16 v[10:13], v[20:23], v[2:5], v[10:13]
	s_nop 4
	s_waitcnt vmcnt(13)
	ds_write_b128 v198, v[32:35]
	ds_write_b128 v198, v[36:39] offset:1152
	ds_read_b128 v[32:35], v199
	ds_read_b128 v[36:39], v199 offset:64
	s_waitcnt lgkmcnt(4)
	v_mfma_f32_16x16x32_f16 v[194:197], v[24:27], v[6:9], 0
	v_mfma_f32_16x16x32_f16 v[194:197], v[28:31], v[2:5], v[194:197]
	v_or_b32_e32 v80, 0, v160
	v_mul_f32_e32 v10, 0x3e000000, v10
	v_mul_f32_e32 v11, 0x3e000000, v11
	v_mul_f32_e32 v12, 0x3e000000, v12
	v_mul_f32_e32 v13, 0x3e000000, v13
	v_lshl_add_u32 v81, v80, 5, v167
	v_max3_f32 v15, v15, v10, v11
	v_max3_f32 v15, v15, v12, v13
	s_and_saveexec_b64 s[2:3], s[38:39]
	ds_write_b32 v81, v10
	ds_write_b32 v81, v11 offset:32
	ds_write_b32 v81, v12 offset:64
	ds_write_b32 v81, v13 offset:96
	s_or_b64 exec, exec, s[2:3]
	s_waitcnt vmcnt(12)
	ds_write_b128 v198, v[40:43]
	ds_write_b128 v198, v[44:47] offset:1152
	ds_read_b128 v[40:43], v199
	ds_read_b128 v[44:47], v199 offset:64
	s_waitcnt lgkmcnt(8)
	v_mfma_f32_16x16x32_f16 v[10:13], v[32:35], v[6:9], 0
	v_mfma_f32_16x16x32_f16 v[10:13], v[36:39], v[2:5], v[10:13]
	v_or_b32_e32 v80, 16, v160
	v_mul_f32_e32 v194, 0x3e000000, v194
	v_mul_f32_e32 v195, 0x3e000000, v195
	v_mul_f32_e32 v196, 0x3e000000, v196
	v_mul_f32_e32 v197, 0x3e000000, v197
	v_lshl_add_u32 v81, v80, 5, v167
	v_max3_f32 v15, v15, v194, v195
	v_max3_f32 v15, v15, v196, v197
	s_and_saveexec_b64 s[2:3], s[38:39]
	ds_write_b32 v81, v194
	ds_write_b32 v81, v195 offset:32
	ds_write_b32 v81, v196 offset:64
	ds_write_b32 v81, v197 offset:96
	s_or_b64 exec, exec, s[2:3]
	s_waitcnt vmcnt(11)
	ds_write_b128 v198, v[48:51]
	ds_write_b128 v198, v[52:55] offset:1152
	ds_read_b128 v[48:51], v199
	ds_read_b128 v[52:55], v199 offset:64
	s_waitcnt lgkmcnt(8)
	v_mfma_f32_16x16x32_f16 v[194:197], v[40:43], v[6:9], 0
	v_mfma_f32_16x16x32_f16 v[194:197], v[44:47], v[2:5], v[194:197]
	v_or_b32_e32 v80, 32, v160
	v_mul_f32_e32 v10, 0x3e000000, v10
	v_mul_f32_e32 v11, 0x3e000000, v11
	v_mul_f32_e32 v12, 0x3e000000, v12
	v_mul_f32_e32 v13, 0x3e000000, v13
	v_lshl_add_u32 v81, v80, 5, v167
	v_max3_f32 v15, v15, v10, v11
	v_max3_f32 v15, v15, v12, v13
	s_and_saveexec_b64 s[2:3], s[38:39]
	ds_write_b32 v81, v10
	ds_write_b32 v81, v11 offset:32
	ds_write_b32 v81, v12 offset:64
	ds_write_b32 v81, v13 offset:96
	s_or_b64 exec, exec, s[2:3]
	s_waitcnt vmcnt(10)
	ds_write_b128 v198, v[56:59]
	ds_write_b128 v198, v[60:63] offset:1152
	ds_read_b128 v[56:59], v199
	ds_read_b128 v[60:63], v199 offset:64
	s_waitcnt lgkmcnt(8)
	v_mfma_f32_16x16x32_f16 v[10:13], v[48:51], v[6:9], 0
	v_mfma_f32_16x16x32_f16 v[10:13], v[52:55], v[2:5], v[10:13]
	v_or_b32_e32 v80, 48, v160
	v_mul_f32_e32 v194, 0x3e000000, v194
	v_mul_f32_e32 v195, 0x3e000000, v195
	v_mul_f32_e32 v196, 0x3e000000, v196
	v_mul_f32_e32 v197, 0x3e000000, v197
	v_lshl_add_u32 v81, v80, 5, v167
	v_max3_f32 v15, v15, v194, v195
	v_max3_f32 v15, v15, v196, v197
	s_and_saveexec_b64 s[2:3], s[38:39]
	ds_write_b32 v81, v194
	ds_write_b32 v81, v195 offset:32
	ds_write_b32 v81, v196 offset:64
	ds_write_b32 v81, v197 offset:96
	s_or_b64 exec, exec, s[2:3]
	s_waitcnt vmcnt(9)
	ds_write_b128 v198, v[64:67]
	ds_write_b128 v198, v[68:71] offset:1152
	ds_read_b128 v[64:67], v199
	ds_read_b128 v[68:71], v199 offset:64
	s_waitcnt lgkmcnt(8)
	v_mfma_f32_16x16x32_f16 v[194:197], v[56:59], v[6:9], 0
	v_mfma_f32_16x16x32_f16 v[194:197], v[60:63], v[2:5], v[194:197]
	v_or_b32_e32 v80, 64, v160
	v_mul_f32_e32 v10, 0x3e000000, v10
	v_mul_f32_e32 v11, 0x3e000000, v11
	v_mul_f32_e32 v12, 0x3e000000, v12
	v_mul_f32_e32 v13, 0x3e000000, v13
	v_lshl_add_u32 v81, v80, 5, v167
	v_max3_f32 v15, v15, v10, v11
	v_max3_f32 v15, v15, v12, v13
	s_and_saveexec_b64 s[2:3], s[38:39]
	ds_write_b32 v81, v10
	ds_write_b32 v81, v11 offset:32
	ds_write_b32 v81, v12 offset:64
	ds_write_b32 v81, v13 offset:96
	s_or_b64 exec, exec, s[2:3]
	s_waitcnt vmcnt(8)
	ds_write_b128 v198, v[72:75]
	ds_write_b128 v198, v[76:79] offset:1152
	ds_read_b128 v[72:75], v199
	ds_read_b128 v[76:79], v199 offset:64
	s_waitcnt lgkmcnt(8)
	v_mfma_f32_16x16x32_f16 v[10:13], v[64:67], v[6:9], 0
	v_mfma_f32_16x16x32_f16 v[10:13], v[68:71], v[2:5], v[10:13]
	v_or_b32_e32 v80, 0x50, v160
	v_mul_f32_e32 v194, 0x3e000000, v194
	v_mul_f32_e32 v195, 0x3e000000, v195
	v_mul_f32_e32 v196, 0x3e000000, v196
	v_mul_f32_e32 v197, 0x3e000000, v197
	v_lshl_add_u32 v81, v80, 5, v167
	v_max3_f32 v15, v15, v194, v195
	v_max3_f32 v15, v15, v196, v197
	s_and_saveexec_b64 s[2:3], s[38:39]
	ds_write_b32 v81, v194
	ds_write_b32 v81, v195 offset:32
	ds_write_b32 v81, v196 offset:64
	ds_write_b32 v81, v197 offset:96
	s_or_b64 exec, exec, s[2:3]
	s_waitcnt vmcnt(7)
	ds_write_b128 v198, v[90:93]
	ds_write_b128 v198, v[94:97] offset:1152
	ds_read_b128 v[90:93], v199
	ds_read_b128 v[94:97], v199 offset:64
	s_waitcnt lgkmcnt(8)
	v_mfma_f32_16x16x32_f16 v[194:197], v[72:75], v[6:9], 0
	v_mfma_f32_16x16x32_f16 v[194:197], v[76:79], v[2:5], v[194:197]
	v_or_b32_e32 v80, 0x60, v160
	v_mul_f32_e32 v10, 0x3e000000, v10
	v_mul_f32_e32 v11, 0x3e000000, v11
	v_mul_f32_e32 v12, 0x3e000000, v12
	v_mul_f32_e32 v13, 0x3e000000, v13
	v_lshl_add_u32 v81, v80, 5, v167
	v_max3_f32 v15, v15, v10, v11
	v_max3_f32 v15, v15, v12, v13
	s_and_saveexec_b64 s[2:3], s[38:39]
	ds_write_b32 v81, v10
	ds_write_b32 v81, v11 offset:32
	ds_write_b32 v81, v12 offset:64
	ds_write_b32 v81, v13 offset:96
	s_or_b64 exec, exec, s[2:3]
	s_waitcnt vmcnt(6)
;   __device__ __forceinline__ half_t* mm() const { return (half_t*)(ws() + OFF_mm); }
; __device__ __forceinline__ void dsa_item(const KP& p, int b, int tile, char* smem) {
;     ...
;       for (int mm = 0; mm < 8; ++mm) {
;         const int m = mg * 8 + mm;
;         const int pos = m * 16 + col;
;         const int s = (pos < nsel) ? (int)sel[tk * 256 + pos] : 0;
;         const half_t* kp = ub + (size_t)s * NU + C_BK + hq * 8;
;         const h8 a0 = *(const h8*)kp, a1 = *(const h8*)(kp + 32);
;         f32x4 d = {0.f, 0.f, 0.f, 0.f};
;         d = __builtin_amdgcn_mfma_f32_16x16x32_f16(a0, q0, d, 0, 0, 0);
;         d = __builtin_amdgcn_mfma_f32_16x16x32_f16(a1, q1, d, 0, 0, 0);
; #pragma unroll
;         for (int r = 0; r < 4; ++r) {
;           const int pp = m * 16 + hq * 4 + r;
;           const float v = (pp < nsel) ? d[r] * 0.125f : NEGF;
;           mx = fmaxf(mx, v);
;           if (col < 8) pbuf[pp * 8 + col] = v;
;         }
	ds_write_b128 v198, v[98:101]
	ds_write_b128 v198, v[102:105] offset:1152
	ds_read_b128 v[98:101], v199
	ds_read_b128 v[102:105], v199 offset:64
	s_waitcnt lgkmcnt(8)
	v_mfma_f32_16x16x32_f16 v[10:13], v[90:93], v[6:9], 0
	v_mfma_f32_16x16x32_f16 v[10:13], v[94:97], v[2:5], v[10:13]
	v_or_b32_e32 v80, 0x70, v160
	v_mul_f32_e32 v194, 0x3e000000, v194
	v_mul_f32_e32 v195, 0x3e000000, v195
	v_mul_f32_e32 v196, 0x3e000000, v196
	v_mul_f32_e32 v197, 0x3e000000, v197
	v_lshl_add_u32 v81, v80, 5, v167
	v_max3_f32 v15, v15, v194, v195
	v_max3_f32 v15, v15, v196, v197
	s_and_saveexec_b64 s[2:3], s[38:39]
	ds_write_b32 v81, v194
	ds_write_b32 v81, v195 offset:32
	ds_write_b32 v81, v196 offset:64
	ds_write_b32 v81, v197 offset:96
	s_or_b64 exec, exec, s[2:3]
	s_waitcnt vmcnt(5)
	ds_write_b128 v198, v[106:109]
	ds_write_b128 v198, v[110:113] offset:1152
	ds_read_b128 v[106:109], v199
	ds_read_b128 v[110:113], v199 offset:64
	s_waitcnt lgkmcnt(8)
	v_mfma_f32_16x16x32_f16 v[194:197], v[98:101], v[6:9], 0
	v_mfma_f32_16x16x32_f16 v[194:197], v[102:105], v[2:5], v[194:197]
	v_or_b32_e32 v80, 0x80, v160
	v_mul_f32_e32 v10, 0x3e000000, v10
	v_mul_f32_e32 v11, 0x3e000000, v11
	v_mul_f32_e32 v12, 0x3e000000, v12
	v_mul_f32_e32 v13, 0x3e000000, v13
	v_lshl_add_u32 v81, v80, 5, v167
	v_max3_f32 v15, v15, v10, v11
	v_max3_f32 v15, v15, v12, v13
	s_and_saveexec_b64 s[2:3], s[38:39]
	ds_write_b32 v81, v10
	ds_write_b32 v81, v11 offset:32
	ds_write_b32 v81, v12 offset:64
	ds_write_b32 v81, v13 offset:96
	s_or_b64 exec, exec, s[2:3]
	s_waitcnt vmcnt(4)
	ds_write_b128 v198, v[114:117]
	ds_write_b128 v198, v[118:121] offset:1152
	ds_read_b128 v[114:117], v199
	ds_read_b128 v[118:121], v199 offset:64
	s_waitcnt lgkmcnt(8)
	v_mfma_f32_16x16x32_f16 v[10:13], v[106:109], v[6:9], 0
	v_mfma_f32_16x16x32_f16 v[10:13], v[110:113], v[2:5], v[10:13]
	v_or_b32_e32 v80, 0x90, v160
	v_mul_f32_e32 v194, 0x3e000000, v194
	v_mul_f32_e32 v195, 0x3e000000, v195
	v_mul_f32_e32 v196, 0x3e000000, v196
	v_mul_f32_e32 v197, 0x3e000000, v197
	v_lshl_add_u32 v81, v80, 5, v167
	v_max3_f32 v15, v15, v194, v195
	v_max3_f32 v15, v15, v196, v197
	s_and_saveexec_b64 s[2:3], s[38:39]
	ds_write_b32 v81, v194
	ds_write_b32 v81, v195 offset:32
	ds_write_b32 v81, v196 offset:64
	ds_write_b32 v81, v197 offset:96
	s_or_b64 exec, exec, s[2:3]
	s_waitcnt vmcnt(3)
	ds_write_b128 v198, v[122:125]
	ds_write_b128 v198, v[128:131] offset:1152
	ds_read_b128 v[122:125], v199
	ds_read_b128 v[128:131], v199 offset:64
	s_waitcnt lgkmcnt(8)
	v_mfma_f32_16x16x32_f16 v[194:197], v[114:117], v[6:9], 0
	v_mfma_f32_16x16x32_f16 v[194:197], v[118:121], v[2:5], v[194:197]
	v_or_b32_e32 v80, 0xa0, v160
	v_mul_f32_e32 v10, 0x3e000000, v10
	v_mul_f32_e32 v11, 0x3e000000, v11
	v_mul_f32_e32 v12, 0x3e000000, v12
	v_mul_f32_e32 v13, 0x3e000000, v13
	v_lshl_add_u32 v81, v80, 5, v167
	v_max3_f32 v15, v15, v10, v11
	v_max3_f32 v15, v15, v12, v13
	s_and_saveexec_b64 s[2:3], s[38:39]
	ds_write_b32 v81, v10
	ds_write_b32 v81, v11 offset:32
	ds_write_b32 v81, v12 offset:64
	ds_write_b32 v81, v13 offset:96
	s_or_b64 exec, exec, s[2:3]
	s_waitcnt vmcnt(2)
	ds_write_b128 v198, v[132:135]
	ds_write_b128 v198, v[136:139] offset:1152
	ds_read_b128 v[132:135], v199
	ds_read_b128 v[136:139], v199 offset:64
	s_waitcnt lgkmcnt(8)
	v_mfma_f32_16x16x32_f16 v[10:13], v[122:125], v[6:9], 0
	v_mfma_f32_16x16x32_f16 v[10:13], v[128:131], v[2:5], v[10:13]
	v_or_b32_e32 v80, 0xb0, v160
	v_mul_f32_e32 v194, 0x3e000000, v194
	v_mul_f32_e32 v195, 0x3e000000, v195
	v_mul_f32_e32 v196, 0x3e000000, v196
	v_mul_f32_e32 v197, 0x3e000000, v197
	v_lshl_add_u32 v81, v80, 5, v167
	v_max3_f32 v15, v15, v194, v195
	v_max3_f32 v15, v15, v196, v197
	s_and_saveexec_b64 s[2:3], s[38:39]
	ds_write_b32 v81, v194
	ds_write_b32 v81, v195 offset:32
	ds_write_b32 v81, v196 offset:64
	ds_write_b32 v81, v197 offset:96
	s_or_b64 exec, exec, s[2:3]
	s_waitcnt vmcnt(1)
	ds_write_b128 v198, v[140:143]
	ds_write_b128 v198, v[144:147] offset:1152
	ds_read_b128 v[140:143], v199
	ds_read_b128 v[144:147], v199 offset:64
	s_waitcnt lgkmcnt(8)
	v_mfma_f32_16x16x32_f16 v[194:197], v[132:135], v[6:9], 0
	v_mfma_f32_16x16x32_f16 v[194:197], v[136:139], v[2:5], v[194:197]
	v_or_b32_e32 v80, 0xc0, v160
	v_mul_f32_e32 v10, 0x3e000000, v10
	v_mul_f32_e32 v11, 0x3e000000, v11
	v_mul_f32_e32 v12, 0x3e000000, v12
	v_mul_f32_e32 v13, 0x3e000000, v13
	v_lshl_add_u32 v81, v80, 5, v167
	v_max3_f32 v15, v15, v10, v11
	v_max3_f32 v15, v15, v12, v13
	s_and_saveexec_b64 s[2:3], s[38:39]
	ds_write_b32 v81, v10
	ds_write_b32 v81, v11 offset:32
	ds_write_b32 v81, v12 offset:64
	ds_write_b32 v81, v13 offset:96
	s_or_b64 exec, exec, s[2:3]
	s_waitcnt vmcnt(0)
	ds_write_b128 v198, v[148:151]
	ds_write_b128 v198, v[152:155] offset:1152
	ds_read_b128 v[148:151], v199
	ds_read_b128 v[152:155], v199 offset:64
	s_waitcnt lgkmcnt(8)
	v_mfma_f32_16x16x32_f16 v[10:13], v[140:143], v[6:9], 0
	v_mfma_f32_16x16x32_f16 v[10:13], v[144:147], v[2:5], v[10:13]
	v_or_b32_e32 v80, 0xd0, v160
	v_mul_f32_e32 v194, 0x3e000000, v194
	v_mul_f32_e32 v195, 0x3e000000, v195
	v_mul_f32_e32 v196, 0x3e000000, v196
	v_mul_f32_e32 v197, 0x3e000000, v197
	v_lshl_add_u32 v81, v80, 5, v167
	v_max3_f32 v15, v15, v194, v195
	v_max3_f32 v15, v15, v196, v197
	s_and_saveexec_b64 s[2:3], s[38:39]
	ds_write_b32 v81, v194
	ds_write_b32 v81, v195 offset:32
	ds_write_b32 v81, v196 offset:64
	ds_write_b32 v81, v197 offset:96
	s_or_b64 exec, exec, s[2:3]
	s_waitcnt lgkmcnt(4)
	v_mfma_f32_16x16x32_f16 v[194:197], v[148:151], v[6:9], 0
	v_mfma_f32_16x16x32_f16 v[194:197], v[152:155], v[2:5], v[194:197]
	v_or_b32_e32 v80, 0xe0, v160
	v_mul_f32_e32 v10, 0x3e000000, v10
	v_mul_f32_e32 v11, 0x3e000000, v11
	v_mul_f32_e32 v12, 0x3e000000, v12
	v_mul_f32_e32 v13, 0x3e000000, v13
	v_lshl_add_u32 v81, v80, 5, v167
	v_max3_f32 v15, v15, v10, v11
	v_max3_f32 v15, v15, v12, v13
	s_and_saveexec_b64 s[2:3], s[38:39]
	ds_write_b32 v81, v10
	ds_write_b32 v81, v11 offset:32
	ds_write_b32 v81, v12 offset:64
	ds_write_b32 v81, v13 offset:96
	s_or_b64 exec, exec, s[2:3]
	s_nop 7
	v_or_b32_e32 v80, 0xf0, v160
	v_mul_f32_e32 v194, 0x3e000000, v194
	v_mul_f32_e32 v195, 0x3e000000, v195
	v_mul_f32_e32 v196, 0x3e000000, v196
	v_mul_f32_e32 v197, 0x3e000000, v197
	v_lshl_add_u32 v81, v80, 5, v167
	v_max3_f32 v15, v15, v194, v195
	v_max3_f32 v15, v15, v196, v197
	s_and_saveexec_b64 s[2:3], s[38:39]
	ds_write_b32 v81, v194
	ds_write_b32 v81, v195 offset:32
	ds_write_b32 v81, v196 offset:64
	ds_write_b32 v81, v197 offset:96
	s_or_b64 exec, exec, s[2:3]

; __device__ __forceinline__ void dsa_item(const KP& p, int b, int tile, char* smem) {
;     ...
;     float sum = 0.f;
; #pragma unroll 4
;     for (int k = 0; k < 32; ++k) {
;       const int i = lane + 64 * k;
;       const float v = pbuf[i];
;       const float e = (v > -1e29f) ? __expf(v - mxh) : 0.f;
;       pbuf[i] = e;
;       sum += e;
;     }
.LBB0_1510:
	ds_read2st64_b32 v[16:17], v168 offset1:1
	ds_read2st64_b32 v[18:19], v168 offset0:2 offset1:3
	ds_read2st64_b32 v[20:21], v168 offset0:4 offset1:5
	ds_read2st64_b32 v[22:23], v168 offset0:6 offset1:7
	ds_read2st64_b32 v[24:25], v168 offset0:8 offset1:9
	ds_read2st64_b32 v[26:27], v168 offset0:10 offset1:11
	ds_read2st64_b32 v[28:29], v168 offset0:12 offset1:13
	ds_read2st64_b32 v[30:31], v168 offset0:14 offset1:15
	ds_read2st64_b32 v[32:33], v168 offset0:16 offset1:17
	ds_read2st64_b32 v[34:35], v168 offset0:18 offset1:19
	ds_read2st64_b32 v[36:37], v168 offset0:20 offset1:21
	ds_read2st64_b32 v[38:39], v168 offset0:22 offset1:23
	ds_read2st64_b32 v[40:41], v168 offset0:24 offset1:25
	ds_read2st64_b32 v[42:43], v168 offset0:26 offset1:27
	ds_read2st64_b32 v[44:45], v168 offset0:28 offset1:29
	ds_read2st64_b32 v[46:47], v168 offset0:30 offset1:31
	v_readfirstlane_b32 s2, v85
	s_nop 1
	s_cmp_eq_u32 s2, 0x100
	s_cbranch_scc1 .Lsm_full
	s_waitcnt lgkmcnt(14)
	v_cmp_lt_f32_e32 vcc, s75, v16
	v_cmp_lt_f32_e64 s[2:3], s75, v17
	v_cmp_lt_f32_e64 s[14:15], s75, v18
	v_cmp_lt_f32_e64 s[46:47], s75, v19
	v_sub_f32_e32 v16, v16, v2
	v_sub_f32_e32 v17, v17, v2
	v_sub_f32_e32 v18, v18, v2
	v_sub_f32_e32 v19, v19, v2
	v_mul_f32_e32 v16, 0x3fb8aa3b, v16
	v_mul_f32_e32 v17, 0x3fb8aa3b, v17
	v_mul_f32_e32 v18, 0x3fb8aa3b, v18
	v_mul_f32_e32 v19, 0x3fb8aa3b, v19
	v_exp_f32_e32 v16, v16
	v_exp_f32_e32 v17, v17
	v_exp_f32_e32 v18, v18
	v_exp_f32_e32 v19, v19
	v_cndmask_b32_e32 v16, 0, v16, vcc
	v_cndmask_b32_e64 v17, 0, v17, s[2:3]
	v_cndmask_b32_e64 v18, 0, v18, s[14:15]
	v_cndmask_b32_e64 v19, 0, v19, s[46:47]
	v_add_f32_e32 v3, v3, v16
	v_add_f32_e32 v3, v3, v17
	v_add_f32_e32 v3, v3, v18
	v_add_f32_e32 v3, v3, v19
	s_waitcnt lgkmcnt(12)
	v_cmp_lt_f32_e32 vcc, s75, v20
	v_cmp_lt_f32_e64 s[2:3], s75, v21
	v_cmp_lt_f32_e64 s[14:15], s75, v22
	v_cmp_lt_f32_e64 s[46:47], s75, v23
	v_sub_f32_e32 v20, v20, v2
	v_sub_f32_e32 v21, v21, v2
	v_sub_f32_e32 v22, v22, v2
	v_sub_f32_e32 v23, v23, v2
	v_mul_f32_e32 v20, 0x3fb8aa3b, v20
	v_mul_f32_e32 v21, 0x3fb8aa3b, v21
	v_mul_f32_e32 v22, 0x3fb8aa3b, v22
	v_mul_f32_e32 v23, 0x3fb8aa3b, v23
	v_exp_f32_e32 v20, v20
	v_exp_f32_e32 v21, v21
	v_exp_f32_e32 v22, v22
	v_exp_f32_e32 v23, v23
	v_cndmask_b32_e32 v20, 0, v20, vcc
	v_cndmask_b32_e64 v21, 0, v21, s[2:3]
	v_cndmask_b32_e64 v22, 0, v22, s[14:15]
	v_cndmask_b32_e64 v23, 0, v23, s[46:47]
	v_add_f32_e32 v3, v3, v20
	v_add_f32_e32 v3, v3, v21
	v_add_f32_e32 v3, v3, v22
	v_add_f32_e32 v3, v3, v23
	s_waitcnt lgkmcnt(10)
	v_cmp_lt_f32_e32 vcc, s75, v24
	v_cmp_lt_f32_e64 s[2:3], s75, v25
	v_cmp_lt_f32_e64 s[14:15], s75, v26
	v_cmp_lt_f32_e64 s[46:47], s75, v27
	v_sub_f32_e32 v24, v24, v2
	v_sub_f32_e32 v25, v25, v2
	v_sub_f32_e32 v26, v26, v2
	v_sub_f32_e32 v27, v27, v2
	v_mul_f32_e32 v24, 0x3fb8aa3b, v24
	v_mul_f32_e32 v25, 0x3fb8aa3b, v25
	v_mul_f32_e32 v26, 0x3fb8aa3b, v26
	v_mul_f32_e32 v27, 0x3fb8aa3b, v27
	v_exp_f32_e32 v24, v24
	v_exp_f32_e32 v25, v25
	v_exp_f32_e32 v26, v26
	v_exp_f32_e32 v27, v27
	v_cndmask_b32_e32 v24, 0, v24, vcc
	v_cndmask_b32_e64 v25, 0, v25, s[2:3]
	v_cndmask_b32_e64 v26, 0, v26, s[14:15]
	v_cndmask_b32_e64 v27, 0, v27, s[46:47]
	v_add_f32_e32 v3, v3, v24
	v_add_f32_e32 v3, v3, v25
	v_add_f32_e32 v3, v3, v26
	v_add_f32_e32 v3, v3, v27
	s_waitcnt lgkmcnt(8)
	v_cmp_lt_f32_e32 vcc, s75, v28
	v_cmp_lt_f32_e64 s[2:3], s75, v29
	v_cmp_lt_f32_e64 s[14:15], s75, v30
	v_cmp_lt_f32_e64 s[46:47], s75, v31
	v_sub_f32_e32 v28, v28, v2
	v_sub_f32_e32 v29, v29, v2
	v_sub_f32_e32 v30, v30, v2
	v_sub_f32_e32 v31, v31, v2
	v_mul_f32_e32 v28, 0x3fb8aa3b, v28
	v_mul_f32_e32 v29, 0x3fb8aa3b, v29
	v_mul_f32_e32 v30, 0x3fb8aa3b, v30
	v_mul_f32_e32 v31, 0x3fb8aa3b, v31
	v_exp_f32_e32 v28, v28
	v_exp_f32_e32 v29, v29
	v_exp_f32_e32 v30, v30
	v_exp_f32_e32 v31, v31
	v_cndmask_b32_e32 v28, 0, v28, vcc
	v_cndmask_b32_e64 v29, 0, v29, s[2:3]
	v_cndmask_b32_e64 v30, 0, v30, s[14:15]
	v_cndmask_b32_e64 v31, 0, v31, s[46:47]
	v_add_f32_e32 v3, v3, v28
	v_add_f32_e32 v3, v3, v29
	v_add_f32_e32 v3, v3, v30
	v_add_f32_e32 v3, v3, v31
	s_waitcnt lgkmcnt(6)
	v_cmp_lt_f32_e32 vcc, s75, v32
	v_cmp_lt_f32_e64 s[2:3], s75, v33
	v_cmp_lt_f32_e64 s[14:15], s75, v34
	v_cmp_lt_f32_e64 s[46:47], s75, v35
	v_sub_f32_e32 v32, v32, v2
	v_sub_f32_e32 v33, v33, v2
	v_sub_f32_e32 v34, v34, v2
	v_sub_f32_e32 v35, v35, v2
	v_mul_f32_e32 v32, 0x3fb8aa3b, v32
	v_mul_f32_e32 v33, 0x3fb8aa3b, v33
	v_mul_f32_e32 v34, 0x3fb8aa3b, v34
	v_mul_f32_e32 v35, 0x3fb8aa3b, v35
	v_exp_f32_e32 v32, v32
	v_exp_f32_e32 v33, v33
	v_exp_f32_e32 v34, v34
	v_exp_f32_e32 v35, v35
	v_cndmask_b32_e32 v32, 0, v32, vcc
	v_cndmask_b32_e64 v33, 0, v33, s[2:3]
	v_cndmask_b32_e64 v34, 0, v34, s[14:15]
	v_cndmask_b32_e64 v35, 0, v35, s[46:47]
	v_add_f32_e32 v3, v3, v32
	v_add_f32_e32 v3, v3, v33
	v_add_f32_e32 v3, v3, v34
	v_add_f32_e32 v3, v3, v35
	s_waitcnt lgkmcnt(4)
	v_cmp_lt_f32_e32 vcc, s75, v36
	v_cmp_lt_f32_e64 s[2:3], s75, v37
	v_cmp_lt_f32_e64 s[14:15], s75, v38
	v_cmp_lt_f32_e64 s[46:47], s75, v39
	v_sub_f32_e32 v36, v36, v2
	v_sub_f32_e32 v37, v37, v2
	v_sub_f32_e32 v38, v38, v2
	v_sub_f32_e32 v39, v39, v2
	v_mul_f32_e32 v36, 0x3fb8aa3b, v36
	v_mul_f32_e32 v37, 0x3fb8aa3b, v37
	v_mul_f32_e32 v38, 0x3fb8aa3b, v38
	v_mul_f32_e32 v39, 0x3fb8aa3b, v39
	v_exp_f32_e32 v36, v36
	v_exp_f32_e32 v37, v37
	v_exp_f32_e32 v38, v38
	v_exp_f32_e32 v39, v39
	v_cndmask_b32_e32 v36, 0, v36, vcc
	v_cndmask_b32_e64 v37, 0, v37, s[2:3]
	v_cndmask_b32_e64 v38, 0, v38, s[14:15]
	v_cndmask_b32_e64 v39, 0, v39, s[46:47]
	v_add_f32_e32 v3, v3, v36
	v_add_f32_e32 v3, v3, v37
	v_add_f32_e32 v3, v3, v38
	v_add_f32_e32 v3, v3, v39
	s_waitcnt lgkmcnt(2)
; __device__ __forceinline__ void dsa_item(const KP& p, int b, int tile, char* smem) {
;     ...
;     float sum = 0.f;
; #pragma unroll 4
;     for (int k = 0; k < 32; ++k) {
;       const int i = lane + 64 * k;
;       const float v = pbuf[i];
;       const float e = (v > -1e29f) ? __expf(v - mxh) : 0.f;
;       pbuf[i] = e;
;       sum += e;
;     }
	v_cmp_lt_f32_e32 vcc, s75, v40
	v_cmp_lt_f32_e64 s[2:3], s75, v41
	v_cmp_lt_f32_e64 s[14:15], s75, v42
	v_cmp_lt_f32_e64 s[46:47], s75, v43
	v_sub_f32_e32 v40, v40, v2
	v_sub_f32_e32 v41, v41, v2
	v_sub_f32_e32 v42, v42, v2
	v_sub_f32_e32 v43, v43, v2
	v_mul_f32_e32 v40, 0x3fb8aa3b, v40
	v_mul_f32_e32 v41, 0x3fb8aa3b, v41
	v_mul_f32_e32 v42, 0x3fb8aa3b, v42
	v_mul_f32_e32 v43, 0x3fb8aa3b, v43
	v_exp_f32_e32 v40, v40
	v_exp_f32_e32 v41, v41
	v_exp_f32_e32 v42, v42
	v_exp_f32_e32 v43, v43
	v_cndmask_b32_e32 v40, 0, v40, vcc
	v_cndmask_b32_e64 v41, 0, v41, s[2:3]
	v_cndmask_b32_e64 v42, 0, v42, s[14:15]
	v_cndmask_b32_e64 v43, 0, v43, s[46:47]
	v_add_f32_e32 v3, v3, v40
	v_add_f32_e32 v3, v3, v41
	v_add_f32_e32 v3, v3, v42
	v_add_f32_e32 v3, v3, v43
	s_waitcnt lgkmcnt(0)
	v_cmp_lt_f32_e32 vcc, s75, v44
	v_cmp_lt_f32_e64 s[2:3], s75, v45
	v_cmp_lt_f32_e64 s[14:15], s75, v46
	v_cmp_lt_f32_e64 s[46:47], s75, v47
	v_sub_f32_e32 v44, v44, v2
	v_sub_f32_e32 v45, v45, v2
	v_sub_f32_e32 v46, v46, v2
	v_sub_f32_e32 v47, v47, v2
	v_mul_f32_e32 v44, 0x3fb8aa3b, v44
	v_mul_f32_e32 v45, 0x3fb8aa3b, v45
	v_mul_f32_e32 v46, 0x3fb8aa3b, v46
	v_mul_f32_e32 v47, 0x3fb8aa3b, v47
	v_exp_f32_e32 v44, v44
	v_exp_f32_e32 v45, v45
	v_exp_f32_e32 v46, v46
	v_exp_f32_e32 v47, v47
	v_cndmask_b32_e32 v44, 0, v44, vcc
	v_cndmask_b32_e64 v45, 0, v45, s[2:3]
	v_cndmask_b32_e64 v46, 0, v46, s[14:15]
	v_cndmask_b32_e64 v47, 0, v47, s[46:47]
	v_add_f32_e32 v3, v3, v44
	v_add_f32_e32 v3, v3, v45
	v_add_f32_e32 v3, v3, v46
	v_add_f32_e32 v3, v3, v47
	s_branch .Lsm_done
.Lsm_full:
	s_waitcnt lgkmcnt(14)
	v_sub_f32_e32 v16, v16, v2
	v_sub_f32_e32 v17, v17, v2
	v_sub_f32_e32 v18, v18, v2
	v_sub_f32_e32 v19, v19, v2
	v_mul_f32_e32 v16, 0x3fb8aa3b, v16
	v_mul_f32_e32 v17, 0x3fb8aa3b, v17
	v_mul_f32_e32 v18, 0x3fb8aa3b, v18
	v_mul_f32_e32 v19, 0x3fb8aa3b, v19
	v_exp_f32_e32 v16, v16
	v_exp_f32_e32 v17, v17
	v_exp_f32_e32 v18, v18
	v_exp_f32_e32 v19, v19
	s_nop 0
	v_add_f32_e32 v3, v3, v16
	v_add_f32_e32 v3, v3, v17
	v_add_f32_e32 v3, v3, v18
	v_add_f32_e32 v3, v3, v19
	s_waitcnt lgkmcnt(12)
	v_sub_f32_e32 v20, v20, v2
	v_sub_f32_e32 v21, v21, v2
	v_sub_f32_e32 v22, v22, v2
	v_sub_f32_e32 v23, v23, v2
	v_mul_f32_e32 v20, 0x3fb8aa3b, v20
	v_mul_f32_e32 v21, 0x3fb8aa3b, v21
	v_mul_f32_e32 v22, 0x3fb8aa3b, v22
	v_mul_f32_e32 v23, 0x3fb8aa3b, v23
	v_exp_f32_e32 v20, v20
	v_exp_f32_e32 v21, v21
	v_exp_f32_e32 v22, v22
	v_exp_f32_e32 v23, v23
	s_nop 0
	v_add_f32_e32 v3, v3, v20
	v_add_f32_e32 v3, v3, v21
	v_add_f32_e32 v3, v3, v22
	v_add_f32_e32 v3, v3, v23
	s_waitcnt lgkmcnt(10)
	v_sub_f32_e32 v24, v24, v2
	v_sub_f32_e32 v25, v25, v2
	v_sub_f32_e32 v26, v26, v2
	v_sub_f32_e32 v27, v27, v2
	v_mul_f32_e32 v24, 0x3fb8aa3b, v24
	v_mul_f32_e32 v25, 0x3fb8aa3b, v25
	v_mul_f32_e32 v26, 0x3fb8aa3b, v26
	v_mul_f32_e32 v27, 0x3fb8aa3b, v27
	v_exp_f32_e32 v24, v24
	v_exp_f32_e32 v25, v25
	v_exp_f32_e32 v26, v26
	v_exp_f32_e32 v27, v27
	s_nop 0
	v_add_f32_e32 v3, v3, v24
	v_add_f32_e32 v3, v3, v25
	v_add_f32_e32 v3, v3, v26
	v_add_f32_e32 v3, v3, v27
	s_waitcnt lgkmcnt(8)
	v_sub_f32_e32 v28, v28, v2
	v_sub_f32_e32 v29, v29, v2
	v_sub_f32_e32 v30, v30, v2
	v_sub_f32_e32 v31, v31, v2
	v_mul_f32_e32 v28, 0x3fb8aa3b, v28
	v_mul_f32_e32 v29, 0x3fb8aa3b, v29
	v_mul_f32_e32 v30, 0x3fb8aa3b, v30
	v_mul_f32_e32 v31, 0x3fb8aa3b, v31
	v_exp_f32_e32 v28, v28
	v_exp_f32_e32 v29, v29
	v_exp_f32_e32 v30, v30
	v_exp_f32_e32 v31, v31
	s_nop 0
	v_add_f32_e32 v3, v3, v28
	v_add_f32_e32 v3, v3, v29
	v_add_f32_e32 v3, v3, v30
	v_add_f32_e32 v3, v3, v31
	s_waitcnt lgkmcnt(6)
	v_sub_f32_e32 v32, v32, v2
	v_sub_f32_e32 v33, v33, v2
	v_sub_f32_e32 v34, v34, v2
	v_sub_f32_e32 v35, v35, v2
	v_mul_f32_e32 v32, 0x3fb8aa3b, v32
	v_mul_f32_e32 v33, 0x3fb8aa3b, v33
	v_mul_f32_e32 v34, 0x3fb8aa3b, v34
	v_mul_f32_e32 v35, 0x3fb8aa3b, v35
	v_exp_f32_e32 v32, v32
	v_exp_f32_e32 v33, v33
	v_exp_f32_e32 v34, v34
	v_exp_f32_e32 v35, v35
	s_nop 0
	v_add_f32_e32 v3, v3, v32
	v_add_f32_e32 v3, v3, v33
	v_add_f32_e32 v3, v3, v34
	v_add_f32_e32 v3, v3, v35
	s_waitcnt lgkmcnt(4)
	v_sub_f32_e32 v36, v36, v2
	v_sub_f32_e32 v37, v37, v2
	v_sub_f32_e32 v38, v38, v2
	v_sub_f32_e32 v39, v39, v2
	v_mul_f32_e32 v36, 0x3fb8aa3b, v36
	v_mul_f32_e32 v37, 0x3fb8aa3b, v37
	v_mul_f32_e32 v38, 0x3fb8aa3b, v38
	v_mul_f32_e32 v39, 0x3fb8aa3b, v39
	v_exp_f32_e32 v36, v36
	v_exp_f32_e32 v37, v37
	v_exp_f32_e32 v38, v38
	v_exp_f32_e32 v39, v39
	s_nop 0
	v_add_f32_e32 v3, v3, v36
	v_add_f32_e32 v3, v3, v37
	v_add_f32_e32 v3, v3, v38
	v_add_f32_e32 v3, v3, v39
	s_waitcnt lgkmcnt(2)
	v_sub_f32_e32 v40, v40, v2
	v_sub_f32_e32 v41, v41, v2
	v_sub_f32_e32 v42, v42, v2
	v_sub_f32_e32 v43, v43, v2
	v_mul_f32_e32 v40, 0x3fb8aa3b, v40
	v_mul_f32_e32 v41, 0x3fb8aa3b, v41
	v_mul_f32_e32 v42, 0x3fb8aa3b, v42
	v_mul_f32_e32 v43, 0x3fb8aa3b, v43
	v_exp_f32_e32 v40, v40
	v_exp_f32_e32 v41, v41
	v_exp_f32_e32 v42, v42
	v_exp_f32_e32 v43, v43
	s_nop 0
	v_add_f32_e32 v3, v3, v40
	v_add_f32_e32 v3, v3, v41
	v_add_f32_e32 v3, v3, v42
	v_add_f32_e32 v3, v3, v43
	s_waitcnt lgkmcnt(0)
	v_sub_f32_e32 v44, v44, v2
	v_sub_f32_e32 v45, v45, v2
	v_sub_f32_e32 v46, v46, v2
	v_sub_f32_e32 v47, v47, v2
	v_mul_f32_e32 v44, 0x3fb8aa3b, v44
	v_mul_f32_e32 v45, 0x3fb8aa3b, v45
	v_mul_f32_e32 v46, 0x3fb8aa3b, v46
	v_mul_f32_e32 v47, 0x3fb8aa3b, v47
	v_exp_f32_e32 v44, v44
	v_exp_f32_e32 v45, v45
	v_exp_f32_e32 v46, v46
	v_exp_f32_e32 v47, v47
	s_nop 0
	v_add_f32_e32 v3, v3, v44
	v_add_f32_e32 v3, v3, v45
	v_add_f32_e32 v3, v3, v46
	v_add_f32_e32 v3, v3, v47
; __device__ __forceinline__ void dsa_item(const KP& p, int b, int tile, char* smem) {
;     ...
;       pbuf[i] = e;
;       sum += e;
;     }
;     sum += __shfl_xor(sum, 8);
;     sum += __shfl_xor(sum, 16);
;     sum += __shfl_xor(sum, 32);
;     const float inv = 1.f / sum;
;     __builtin_amdgcn_wave_barrier();
;     {
;       const int rs = lane >> 3, dc = lane & 7;
;       float acc[8][8];
; #pragma unroll
;       for (int h = 0; h < 8; ++h)
; #pragma unroll
;         for (int e = 0; e < 8; ++e) acc[h][e] = 0.f;
.Lsm_done:
	ds_write2st64_b32 v168, v16, v17 offset1:1
	ds_write2st64_b32 v168, v18, v19 offset0:2 offset1:3
	ds_write2st64_b32 v168, v20, v21 offset0:4 offset1:5
	ds_write2st64_b32 v168, v22, v23 offset0:6 offset1:7
	ds_write2st64_b32 v168, v24, v25 offset0:8 offset1:9
	ds_write2st64_b32 v168, v26, v27 offset0:10 offset1:11
	ds_write2st64_b32 v168, v28, v29 offset0:12 offset1:13
	ds_write2st64_b32 v168, v30, v31 offset0:14 offset1:15
	ds_write2st64_b32 v168, v32, v33 offset0:16 offset1:17
	ds_write2st64_b32 v168, v34, v35 offset0:18 offset1:19
	ds_write2st64_b32 v168, v36, v37 offset0:20 offset1:21
	ds_write2st64_b32 v168, v38, v39 offset0:22 offset1:23
	ds_write2st64_b32 v168, v40, v41 offset0:24 offset1:25
	ds_write2st64_b32 v168, v42, v43 offset0:26 offset1:27
	ds_write2st64_b32 v168, v44, v45 offset0:28 offset1:29
	ds_write2st64_b32 v168, v46, v47 offset0:30 offset1:31
	ds_bpermute_b32 v2, v164, v3
	v_mov_b32_e32 v98, 0
	s_mov_b32 s14, 0
	v_mov_b32_e32 v127, v170
	v_mov_b32_e32 v172, v169
	s_waitcnt lgkmcnt(0)
	v_add_f32_e32 v171, v3, v2
	ds_bpermute_b32 v173, v161, v171
	v_mov_b32_e32 v99, v98
	v_mov_b32_e32 v92, v98
	v_mov_b32_e32 v93, v98
	v_mov_b32_e32 v96, v98
	v_mov_b32_e32 v97, v98
	v_mov_b32_e32 v102, v98
	v_mov_b32_e32 v103, v98
	v_mov_b32_e32 v90, v98
	v_mov_b32_e32 v91, v98
	v_mov_b32_e32 v94, v98
	v_mov_b32_e32 v95, v98
	v_mov_b32_e32 v100, v98
	v_mov_b32_e32 v101, v98
	v_mov_b32_e32 v108, v98
	v_mov_b32_e32 v109, v98
	v_mov_b32_e32 v114, v98
	v_mov_b32_e32 v115, v98
	v_mov_b32_e32 v106, v98
	v_mov_b32_e32 v107, v98
	v_mov_b32_e32 v112, v98
	v_mov_b32_e32 v113, v98
	v_mov_b32_e32 v118, v98
	v_mov_b32_e32 v119, v98
	v_mov_b32_e32 v104, v98
	v_mov_b32_e32 v105, v98
	v_mov_b32_e32 v110, v98
	v_mov_b32_e32 v111, v98
	v_mov_b32_e32 v116, v98
	v_mov_b32_e32 v117, v98
	v_mov_b32_e32 v124, v98
	v_mov_b32_e32 v125, v98
	v_mov_b32_e32 v132, v98
	v_mov_b32_e32 v133, v98
	v_mov_b32_e32 v122, v98
	v_mov_b32_e32 v123, v98
	v_mov_b32_e32 v130, v98
	v_mov_b32_e32 v131, v98
	v_mov_b32_e32 v136, v98
	v_mov_b32_e32 v137, v98
	v_mov_b32_e32 v120, v98
	v_mov_b32_e32 v121, v98
	v_mov_b32_e32 v128, v98
	v_mov_b32_e32 v129, v98
	v_mov_b32_e32 v134, v98
	v_mov_b32_e32 v135, v98
	v_mov_b32_e32 v142, v98
	v_mov_b32_e32 v143, v98
	v_mov_b32_e32 v148, v98
	v_mov_b32_e32 v149, v98
	v_mov_b32_e32 v138, v98
	v_mov_b32_e32 v139, v98
	v_mov_b32_e32 v144, v98
	v_mov_b32_e32 v145, v98
	v_mov_b32_e32 v150, v98
	v_mov_b32_e32 v151, v98
	v_mov_b32_e32 v140, v98
	v_mov_b32_e32 v141, v98
	v_mov_b32_e32 v146, v98
	v_mov_b32_e32 v147, v98
	v_mov_b32_e32 v152, v98
	v_mov_b32_e32 v153, v98
	v_mov_b32_e32 v154, v98
	v_mov_b32_e32 v155, v98
	s_branch .LBB0_1513
